# phases 2/3 overlapped with attention: the two grid barriers around phase 3 replaced by arrival counters; blocks without a compression tile start differential-attention units right after the in-proj ba
# speedup vs baseline: 1.0122x; 1.0057x over previous
; DI unsigned xb_ld(unsigned* p) { return __hip_atomic_load(p, __ATOMIC_RELAXED, __HIP_MEMORY_SCOPE_AGENT); }
; DI unsigned xb_add(unsigned* p, unsigned v) { return __hip_atomic_fetch_add(p, v, __ATOMIC_RELAXED, __HIP_MEMORY_SCOPE_AGENT); }
; #define XB_SPIN(cond, bar) do { unsigned _sp = 0; while (cond) { __builtin_amdgcn_s_sleep(1); \
;     if ((++_sp & 255u) == 0u) { if (xb_ld(&(bar)[XB_TMO])) break; if (_sp > XB_SPIN_CAP) { atomicAdd(&(bar)[XB_TMO], 1u); break; } } } } while (0)
; DI void xcd_barrier(const XcdBarrier& b) {
;     asm volatile("s_waitcnt vmcnt(0)" ::: "memory");
;     __syncthreads();
;     if (threadIdx.x == 0) {
;         unsigned* bar = b.bar;
;         __builtin_amdgcn_s_waitcnt(0);
;         unsigned nloc = b.st[0], nx = b.st[1];
;         if (nloc == 0u) { xcd_barrier_complete(bar, b.x, nloc, nx); b.st[0] = nloc; b.st[1] = nx; }
;         const unsigned old = xb_add(&bar[XB_XSUB(b.x)], 1u);
;         const unsigned gen = old / nloc;
;         if (old + 1u == (gen + 1u) * nloc) {
;             __builtin_amdgcn_fence(__ATOMIC_RELEASE, "agent");
;             asm volatile("s_waitcnt vmcnt(0)" ::: "memory");
;             const unsigned og = xb_add(&bar[XB_TOP], 1u);
;             const unsigned tg = og / nx;
;             if (og + 1u == (tg + 1u) * nx) xb_add(&bar[XB_TOPGEN], 1u);
;             else XB_SPIN(xb_ld(&bar[XB_TOPGEN]) == tg, bar);
;             __builtin_amdgcn_fence(__ATOMIC_ACQUIRE, "agent");
;             xb_add(&bar[XB_XGEN(b.x)], 1u);
;             asm volatile("s_waitcnt vmcnt(0)" ::: "memory");
;         } else {
;             XB_SPIN(xb_ld(&bar[XB_XGEN(b.x)]) == gen, bar);
;             __builtin_amdgcn_fence(__ATOMIC_ACQUIRE, "agent");
;             asm volatile("s_waitcnt vmcnt(0)" ::: "memory");
;         }
;     }
;     __syncthreads();
; }
.LBB0_340:
	v_readlane_b32 s0, v238, 0
	s_cmpk_gt_i32 s0, 127
	s_cbranch_scc1 .Lp2_nosig
	s_waitcnt vmcnt(0)
	s_barrier
	v_and_b32_e32 v1, 0x3ff, v0
	v_cmp_eq_u32_e32 vcc, 0, v1
	s_and_saveexec_b64 s[0:1], vcc
	s_cbranch_execz .Lp2_sigdone
	buffer_wbl2 sc1
	s_waitcnt vmcnt(0)
	v_mov_b32_e32 v2, 0x1000
	v_mov_b32_e32 v3, 1
	global_atomic_add v2, v3, s[88:89]
	s_waitcnt vmcnt(0)

;     const int tid = VTID, lane = tid & 63, w = __builtin_amdgcn_readfirstlane(tid >> 6), wr = w >> 1, wc = w & 1, r = lane & 31, h = lane >> 5;
;     const int row0 = 8 * w + (lane >> 3), kch = (lane & 7) ^ ((row0 >> 1) & 7);
;     const bf16_t* ga = Ag + (size_t)row0 * lda + kch * 8;
;     const bf16_t* gb = Bg + (size_t)row0 * ldb + kch * 8;
;     unsigned char* st0 = lds + w * 1024;
;     unsigned char* st1 = lds + DSTAGE + w * 1024;
;     int ao[4], bo[4];
;     {
;         const int ra = wr * 64 + r, rb = wc * 64 + r;
;         const int xa = h ^ ((ra >> 1) & 7), xb = h ^ ((rb >> 1) & 7);
; #pragma unroll
;         for (int s = 0; s < 4; ++s) { ao[s] = ra * 128 + ((xa ^ (2 * s)) << 4); bo[s] = rb * 128 + ((xb ^ (2 * s)) << 4); }
;     }
; DI void phase3(const Params& p, unsigned char* lds) {
;     unsigned char* hl = lds + VHALF * HALF_LDS;
;     for (int t = blockIdx.x; t < 64; t += gridDim.x) {
;         const int kv = t >> 5, bg = (t >> 1) & 15, mt = t & 1, kh = VHALF * 128;
;         const bf16_t* A = (const bf16_t*)(p.ws + OFF_HID) + (size_t)(kv * 16 + bg) * 65536 + (size_t)mt * 128 * 256 + kh;
;         const bf16_t* B = (const bf16_t*)(p.ws + OFF_W2T) + (size_t)kv * 128 * 256 + kh;
;         f32x16 acc[2][2]; zero_acc(acc);
;         if (kv == 0) { gemm_main<false>(A, 256, B, 256, 128, acc, hl); acc_to_lds<false>(acc, hl); }
.Lp2_nosig:
.LBB0_390:
	s_cmp_gt_i32 s90, 3
	s_cselect_b64 s[0:1], -1, 0
	s_cmp_lt_i32 s91, 4
	s_cselect_b64 s[2:3], -1, 0
	s_or_b64 s[0:1], s[0:1], s[2:3]
	s_and_b64 vcc, exec, s[0:1]
	s_cbranch_vccnz .LBB0_456
	v_readlane_b32 s0, v238, 0
	s_cmp_gt_i32 s0, 63
	v_and_b32_e32 v1, 0x3ff, v0
	s_cbranch_scc1 .LBB0_406
.Lp3_wait:
	v_mov_b32_e32 v2, 0x1000
	global_load_dword v2, v2, s[88:89] sc1
	s_waitcnt vmcnt(0)
	v_readfirstlane_b32 s0, v2
	s_cmp_ge_u32 s0, 128
	s_cbranch_scc1 .Lp3_go
	s_sleep 2
	s_branch .Lp3_wait
.Lp3_go:
	buffer_inv sc1
	v_lshrrev_b32_e32 v3, 1, v1
	v_bfe_u32 v4, v1, 5, 1
	v_lshrrev_b32_e32 v2, 8, v1
	s_mov_b32 s0, 0x12000
	v_bitop3_b32 v4, v4, v3, 7 bitop3:0x78
	v_lshrrev_b32_e32 v6, 3, v1
	v_mad_u32_u24 v80, v2, s0, 0
	v_and_b32_e32 v2, 0x180, v3
	v_lshlrev_b32_e32 v82, 4, v4
	v_and_b32_e32 v4, 4, v6
	v_and_b32_e32 v3, 64, v3
	v_and_or_b32 v5, v1, 64, v4
	v_lshl_add_u32 v7, v3, 2, v80
	v_or_b32_e32 v3, v3, v4
	v_and_b32_e32 v4, 0x5f, v1
	v_and_b32_e32 v81, 31, v1
	v_lshlrev_b32_e32 v4, 2, v4
	v_mul_u32_u24_e32 v3, 0x210, v3
	v_mov_b32_e32 v67, 0
	v_lshlrev_b32_e32 v8, 2, v81
	v_mul_u32_u24_e32 v5, 0x210, v5
	v_add3_u32 v88, v80, v4, v3
	v_lshlrev_b32_e32 v66, 1, v2
	v_and_b32_e32 v3, 7, v1
	v_add3_u32 v87, v7, v8, v5
	v_lshl_add_u64 v[4:5], s[88:89], 0, v[66:67]
	s_mov_b64 s[2:3], 0x1a85000
	v_lshlrev_b32_e32 v66, 4, v3
	v_lshl_add_u64 v[68:69], v[4:5], 0, s[2:3]
	v_lshl_add_u64 v[4:5], s[88:89], 0, v[66:67]
	s_mov_b64 s[2:3], 0x19325800
	v_lshl_add_u64 v[70:71], v[4:5], 0, s[2:3]
	v_lshrrev_b32_e32 v4, 4, v1
	v_lshlrev_b32_e32 v5, 3, v1
	v_and_or_b32 v7, v5, 64, v4
	v_readlane_b32 s2, v238, 10
	v_and_b32_e32 v5, 15, v1
	s_add_u32 s24, s88, 0x18ea5800
	v_readlane_b32 s3, v238, 11
	v_mul_u32_u24_e32 v4, 0x210, v4
	v_lshlrev_b32_e32 v5, 5, v5
	v_lshl_or_b32 v66, v6, 7, v66
	s_addc_u32 s25, s89, 0
	s_lshl_b32 s27, s2, 7
	v_add3_u32 v90, v4, v5, 0
	v_lshl_add_u64 v[4:5], s[88:89], 0, v[66:67]
	s_mov_b64 s[2:3], 0x192a5800
	v_readlane_b32 s28, v238, 0
	v_lshl_add_u64 v[72:73], v[4:5], 0, s[2:3]
	v_mul_u32_u24_e32 v4, 0x210, v6
	v_lshlrev_b32_e32 v3, 5, v3
	s_mov_b32 s1, 0
	v_xor_b32_e32 v83, 32, v82
	v_xor_b32_e32 v84, 64, v82
	v_xor_b32_e32 v85, 0x60, v82
	v_bfe_u32 v86, v1, 3, 3
	v_add_u32_e32 v89, 0xfffffe00, v1
	s_lshl_b32 s26, s28, 7
	v_add3_u32 v91, v4, v3, 0
	v_lshlrev_b32_e32 v74, 1, v2
	v_mov_b32_e32 v75, v67
	s_mov_b64 s[2:3], 0x4000
	s_mov_b64 s[4:5], 0x8000
	s_mov_b64 s[6:7], 0xc000
	s_mov_b64 s[8:9], 0x80
	s_mov_b64 s[10:11], 0x4080
	s_mov_b64 s[12:13], 0x8080
	s_mov_b64 s[14:15], 0xc080
	v_lshlrev_b32_e32 v92, 7, v7
	s_mov_b64 s[16:17], 0x1000
	s_mov_b64 s[18:19], 0x2000
	v_add_u32_e32 v93, 0x400, v87
	v_add_u32_e32 v94, 0x1000, v87
	v_add_u32_e32 v95, 0x1400, v87
	v_add_u32_e32 v96, 0x2000, v87
	v_add_u32_e32 v97, 0x2400, v87
	v_add_u32_e32 v98, 0x3000, v87
	v_add_u32_e32 v99, 0x3200, v87
	v_add_u32_e32 v100, 0x3400, v87
	v_add_u32_e32 v101, 0x3600, v87
	v_add_u32_e32 v102, 0x4000, v87
	v_add_u32_e32 v103, 0x4400, v87
	v_add_u32_e32 v104, 0x4800, v87
	v_add_u32_e32 v105, 0x5000, v87
	v_add_u32_e32 v106, 0x5400, v87
	v_add_u32_e32 v107, 0x5800, v87
	v_add_u32_e32 v108, 0x6000, v87
	v_add_u32_e32 v109, 0x6400, v87
	v_add_u32_e32 v110, 0x6800, v87
	v_add_u32_e32 v111, 0x7200, v87
	v_add_u32_e32 v112, 0x7400, v87
	v_add_u32_e32 v113, 0x7600, v87
	v_add_u32_e32 v114, 0x7800, v87
	s_branch .LBB0_394

; DI unsigned xb_ld(unsigned* p) { return __hip_atomic_load(p, __ATOMIC_RELAXED, __HIP_MEMORY_SCOPE_AGENT); }
; DI unsigned xb_add(unsigned* p, unsigned v) { return __hip_atomic_fetch_add(p, v, __ATOMIC_RELAXED, __HIP_MEMORY_SCOPE_AGENT); }
; #define XB_SPIN(cond, bar) do { unsigned _sp = 0; while (cond) { __builtin_amdgcn_s_sleep(1); \
;     if ((++_sp & 255u) == 0u) { if (xb_ld(&(bar)[XB_TMO])) break; if (_sp > XB_SPIN_CAP) { atomicAdd(&(bar)[XB_TMO], 1u); break; } } } } while (0)
; DI void xcd_barrier(const XcdBarrier& b) {
;     asm volatile("s_waitcnt vmcnt(0)" ::: "memory");
;     __syncthreads();
;     if (threadIdx.x == 0) {
;         unsigned* bar = b.bar;
;         __builtin_amdgcn_s_waitcnt(0);
;         unsigned nloc = b.st[0], nx = b.st[1];
;         if (nloc == 0u) { xcd_barrier_complete(bar, b.x, nloc, nx); b.st[0] = nloc; b.st[1] = nx; }
;         const unsigned old = xb_add(&bar[XB_XSUB(b.x)], 1u);
;         const unsigned gen = old / nloc;
;         if (old + 1u == (gen + 1u) * nloc) {
;             __builtin_amdgcn_fence(__ATOMIC_RELEASE, "agent");
;             asm volatile("s_waitcnt vmcnt(0)" ::: "memory");
;             const unsigned og = xb_add(&bar[XB_TOP], 1u);
;             const unsigned tg = og / nx;
;             if (og + 1u == (tg + 1u) * nx) xb_add(&bar[XB_TOPGEN], 1u);
;             else XB_SPIN(xb_ld(&bar[XB_TOPGEN]) == tg, bar);
;             __builtin_amdgcn_fence(__ATOMIC_ACQUIRE, "agent");
;             xb_add(&bar[XB_XGEN(b.x)], 1u);
;             asm volatile("s_waitcnt vmcnt(0)" ::: "memory");
;         } else {
;             XB_SPIN(xb_ld(&bar[XB_XGEN(b.x)]) == gen, bar);
;             __builtin_amdgcn_fence(__ATOMIC_ACQUIRE, "agent");
;             asm volatile("s_waitcnt vmcnt(0)" ::: "memory");
;         }
;     }
;     __syncthreads();
; }
.LBB0_406:
	v_readlane_b32 s0, v238, 0
	s_cmpk_gt_i32 s0, 63
	s_cbranch_scc1 .Lp3s_nosig
	s_waitcnt vmcnt(0)
	s_barrier
	v_and_b32_e32 v1, 0x3ff, v0
	v_cmp_eq_u32_e32 vcc, 0, v1
	s_and_saveexec_b64 s[0:1], vcc
	s_cbranch_execz .Lp3s_sigdone
	buffer_wbl2 sc1
	s_waitcnt vmcnt(0)
	v_mov_b32_e32 v2, 0x1100
	v_mov_b32_e32 v3, 1
	global_atomic_add v2, v3, s[88:89]
	s_waitcnt vmcnt(0)

; #define RUN_PHASE(n, call) if (p.ph_lo <= (n) && (n) < p.ph_hi) { if (PH_ON(n)) { call; } if ((n) + 1 < p.ph_hi) { xcd_barrier(xb); if (PROBE_MODE == 1) xcd_barrier(xb); } }
; __global__ void __launch_bounds__(512, 2) mega(Params p) {
;     ...
;     RUN_PHASE(0, phase0(p, lds))
;     RUN_PHASE(1, phase1(p, lds))
;     RUN_PHASE(2, phase2(p, lds))
;     RUN_PHASE(3, phase3(p, lds))
;     RUN_PHASE(4, phase4(p, lds))
.Lp3s_nosig:
.LBB0_456:
	s_cmp_gt_i32 s90, 4
	s_cselect_b64 s[0:1], -1, 0
	s_cmp_lt_i32 s91, 5
	s_cselect_b64 s[2:3], -1, 0
	s_or_b64 s[0:1], s[0:1], s[2:3]
	s_and_b64 vcc, exec, s[0:1]
	s_cbranch_vccnz .LBB0_627
	v_and_b32_e32 v1, 0x3ff, v0
	v_readfirstlane_b32 s54, v0
	s_bfe_u32 s54, s54, 0x10008

;     int tid_ = threadIdx.x; asm volatile("" : "+v"(tid_));
;     const int lane = tid_ & 63, w = tid_ >> 6, r = lane & 31, h = lane >> 5;
;     const int qt = 15 - (u >> 5), bh = u & 31, b = bh >> 2, hh = bh & 3;
;     const int q0 = qt * 256, wq0 = q0 + 32 * w, qpos = wq0 + r;
;     const int ntl = 4 * qt + 4;
;     const float lam = ((const float*)(p.ws + OFF_CTL))[16];
;     const bf16_t* VTb = (const bf16_t*)(p.ws + OFF_VDT) + (size_t)(b * 4 + hh) * 128 * 4096;
; #pragma unroll 1
;     for (int mp = 0; mp < 2; ++mp) {
;         const size_t hoff = ((size_t)(b * 8 + hh * 2 + mp) * 4096) * 64;
;         const bf16_t* Qb = (const bf16_t*)(p.ws + OFF_QD) + hoff;
;         const bf16_t* Kb = (const bf16_t*)(p.ws + OFF_KD) + hoff;
	s_add_u32 s8, s88, 0xdba5800
	v_lshlrev_b32_e32 v158, 3, v1
	v_lshlrev_b32_e32 v2, 4, v1
	v_or_b32_e32 v6, 0x200, v1
	s_addc_u32 s9, s89, 0
	v_bfe_u32 v187, v0, 3, 7
	v_and_b32_e32 v196, 0x60, v2
	v_and_b32_e32 v197, 8, v158
	v_lshrrev_b32_e32 v6, 3, v6
	s_add_u32 s10, s88, 0xfba5800
	v_mov_b32_e32 v3, 0
	s_movk_i32 s2, 0x90
	v_mul_u32_u24_e32 v159, 0x90, v187
	v_add3_u32 v5, 0, v196, v197
	v_mul_u32_u24_e32 v180, 0x90, v6
	s_addc_u32 s11, s89, 0
	s_mov_b64 s[6:7], src_shared_base
	v_and_b32_e32 v4, 56, v158
	v_mad_u32_u24 v194, v187, s2, 0
	v_and_b32_e32 v195, 0x70, v2
	v_lshl_add_u64 v[6:7], s[88:89], 0, v[2:3]
	s_mov_b64 s[2:3], 0x11ba5800
	s_add_u32 s12, s88, 0x5ba5800
	v_add_u32_e32 v2, v5, v159
	v_add_u32_e32 v5, v5, v180
	v_cmp_eq_u32_e64 s[0:1], 0, v1
	v_lshlrev_b32_e32 v170, 7, v187
	v_mov_b32_e32 v171, v3
	s_movk_i32 s26, 0x200
	v_lshl_add_u64 v[160:161], v[6:7], 0, s[2:3]
	s_addc_u32 s13, s89, 0
	s_mov_b64 s[14:15], 0
	s_add_i32 s33, 0, 0x24010
	s_mov_b64 s[16:17], 0x2000
	v_add_u32_e32 v198, v194, v195
	s_mov_b32 s6, 0x3e38aa3b
	s_mov_b32 s27, 0x40e66666
	v_mov_b32_e32 v181, 0x358637bd
	s_mov_b32 s28, 0x800000
	v_lshlrev_b32_e32 v172, 1, v4
	v_add_u32_e32 v182, 0x2000, v2
	v_add_u32_e32 v183, 0x2000, v5
	v_mov_b32_e32 v184, 0xff800000
	s_branch .LBB0_460

;     int tid_ = threadIdx.x; asm volatile("" : "+v"(tid_));
;     const int lane = tid_ & 63, w = tid_ >> 6, r = lane & 31, h = lane >> 5;
;     const int qt = 63 - (u >> 4), bg = u & 15, b = bg >> 1, g = bg & 1;
;     const int hq = w >> 2, q0 = qt * 64, qb = q0 + 32 * hq, qpos = qb + r, head = g * 4 + (w & 3);
;     float* IMPW = (float*)(lds + NSA_IMPW);
;     u64* SEL = (u64*)(lds + NSA_SEL);
;     u64* UN = (u64*)(lds + NSA_UN);
;     const bf16_t* Qb = (const bf16_t*)(p.ws + OFF_QN) + ((size_t)(b * 8 + head) * 4096) * 64;
;     bf16x8 qf[4];
; #pragma unroll
;     for (int s = 0; s < 4; ++s) qf[s] = *(const bf16x8*)(Qb + (size_t)qpos * 64 + s * 16 + h * 8);
; #pragma unroll
;     for (int s = 0; s < 4; ++s) asm volatile("" : "+v"(qf[s]));
;     const float* gp = (const float*)(p.ws + OFF_GATES) + ((size_t)b * 4096 + qpos) * 24 + head * 3;
;     ...
;     if (which & 2) for (;;) {
;         if (threadIdx.x == 0) *su = (int)atomicAdd(counter + 1, 1u);
;         __syncthreads();
;         const int u = *su;
;         __syncthreads();
;         if (u >= 1024) break;
;         nsa_unit(p, u, lds, probe);
.Lp4n_wait:
	v_mov_b32_e32 v2, 0x1100
	global_load_dword v2, v2, s[88:89] sc1
	s_waitcnt vmcnt(0)
	v_readfirstlane_b32 s2, v2
	s_cmp_ge_u32 s2, 64
	s_cbranch_scc1 .Lp4n_go
	s_sleep 2
	s_branch .Lp4n_wait
.Lp4n_go:
	buffer_inv sc1
	s_add_u32 s2, s88, 0x13ba5800
	s_addc_u32 s3, s89, 0
	v_writelane_b32 v238, s2, 47
	v_mov_b32_e32 v173, 0
	v_lshlrev_b32_e32 v174, 1, v158
	v_writelane_b32 v238, s3, 48
	s_add_u32 s2, s88, 0x192a5800
	s_addc_u32 s3, s89, 0
	v_writelane_b32 v238, s2, 49
	v_mov_b32_e32 v175, v173
	s_add_u32 s76, s88, 0x18ba5800
	v_writelane_b32 v238, s3, 50
	v_lshl_add_u64 v[2:3], s[88:89], 0, v[174:175]
	s_mov_b64 s[2:3], 0x19325800
	s_addc_u32 s77, s89, 0
	v_lshl_add_u64 v[176:177], v[2:3], 0, s[2:3]
	s_add_u32 s2, s88, 0x173a5800
	s_addc_u32 s3, s89, 0
	v_writelane_b32 v238, s2, 51
	v_add_u32_e32 v4, v194, v196
	s_mov_b64 s[70:71], src_shared_base
	v_writelane_b32 v238, s3, 52
	s_add_u32 s2, s88, 0x16ba5800
	s_addc_u32 s3, s89, 0
	s_add_u32 s82, s88, 0x17ba5800
	s_addc_u32 s83, s89, 0
	v_writelane_b32 v238, s2, 53
	s_add_u32 s96, s88, 0x183a5800
	s_addc_u32 s97, s89, 0
	v_writelane_b32 v238, s3, 54
	s_add_i32 s2, 0, 0x19210
	v_add_u32_e32 v2, v4, v197
	v_writelane_b32 v238, s2, 55
	s_add_i32 s2, 0, 0x19220
	s_mov_b64 s[92:93], 0
	s_mov_b32 s69, 0
	s_add_i32 s74, 0, 0x19240
	s_mov_b32 s70, 0x3e38aa3b
	s_add_i32 s75, 0, 0x19000
	v_writelane_b32 v238, s2, 56
	s_add_i32 s2, 0, 0x19230
	s_mov_b32 s78, 0x40e66666
	v_add_u32_e32 v199, 0x2000, v2
	v_mov_b32_e32 v200, 0xff800000
	v_mov_b32_e32 v201, 0x7f800000
	v_writelane_b32 v238, s2, 57
	s_branch .LBB0_486
